# v19: v16 + attention T-loop: S-chain K-fragment ds_reads issued right after the barrier, ahead of the global-load address block
# speedup vs baseline: 1.0102x; 1.0102x over previous
.LBB0_298:
	v_add_u32_e32 v210, s54, v200
	v_add_u32_e32 v66, 0x80, v210
	v_mov_b32_e32 v67, v97
	s_waitcnt lgkmcnt(0)
	s_barrier
	s_bitcmp1_b32 s56, 0
	s_cselect_b32 s57, 0x11000, 0
	v_add_u32_e32 v126, s57, v199
	v_add_u32_e32 v76, s51, v126
	v_add_u32_e32 v152, v76, v166
	ds_read_b128 v[114:117], v152
	ds_read_b128 v[118:121], v152 offset:32
	ds_read_b128 v[122:125], v152 offset:64
	ds_read_b128 v[204:207], v152 offset:96
	v_lshl_add_u64 v[64:65], v[96:97], 1, s[28:29]
	v_lshl_add_u64 v[66:67], v[66:67], 1, s[30:31]
	v_mov_b32_e32 v173, v97
	v_add_u32_e32 v211, s54, v201
	global_load_dwordx4 v[134:137], v[64:65], off offset:2048
	global_load_dwordx4 v[130:133], v[66:67], off
	v_lshl_add_u64 v[64:65], v[172:173], 1, s[28:29]
	v_add_u32_e32 v66, 0x80, v211
	v_mov_b32_e32 v67, v97
	v_lshl_add_u64 v[66:67], v[66:67], 1, s[30:31]
	global_load_dwordx4 v[142:145], v[64:65], off offset:2048
	global_load_dwordx4 v[138:141], v[66:67], off
	s_cmp_gt_u32 s54, s15
	s_cselect_b64 vcc, -1, 0
	s_cmp_lt_i32 s54, s52
	v_mov_b32_e32 v65, s14
	s_cselect_b64 s[0:1], -1, 0
	v_mov_b32_e32 v64, s46
	v_cndmask_b32_e64 v65, 0, v65, s[0:1]
	v_cndmask_b32_e32 v64, v65, v64, vcc
	v_mov_b32_e32 v65, v64
	v_mov_b32_e32 v66, v64
	v_mov_b32_e32 v67, v64
	v_mov_b32_e32 v68, v64
	v_mov_b32_e32 v69, v64
	v_mov_b32_e32 v70, v64
	v_mov_b32_e32 v71, v64
	v_mov_b32_e32 v72, v64
	v_mov_b32_e32 v73, v64
	v_mov_b32_e32 v74, v64
	v_mov_b32_e32 v75, v64
	v_mov_b32_e32 v76, v64
	v_mov_b32_e32 v77, v64
	v_mov_b32_e32 v78, v64
	v_mov_b32_e32 v79, v64
	s_waitcnt lgkmcnt(3)
	s_nop 0
	v_mfma_f32_32x32x16_bf16 v[80:95], v[114:117], v[98:101], v[64:79]
	s_waitcnt lgkmcnt(2)
	v_mfma_f32_32x32x16_bf16 v[80:95], v[118:121], v[102:105], v[80:95]
	s_waitcnt lgkmcnt(1)
	v_mfma_f32_32x32x16_bf16 v[80:95], v[122:125], v[106:109], v[80:95]
	ds_read_b128 v[122:125], v152 offset:8704
	ds_read_b128 v[118:121], v152 offset:8736
	ds_read_b128 v[114:117], v152 offset:8768
	ds_read_b128 v[146:149], v152 offset:8800
	s_waitcnt lgkmcnt(4)
	v_mfma_f32_32x32x16_bf16 v[80:95], v[204:207], v[110:113], v[80:95]
	s_or_b64 s[0:1], vcc, s[0:1]
	s_and_b64 vcc, exec, s[0:1]
	v_add_u32_e32 v151, s55, v202
	s_cbranch_vccnz .LBB0_300
	v_add_u32_e32 v128, 0x2403c, v151
	v_add_u32_e32 v154, 0x24044, v151
	v_add_u32_e32 v156, 0x2405c, v151
	v_add_u32_e32 v158, 0x24064, v151
	v_add_u32_e32 v127, 0x23ffc, v151
	v_add_u32_e32 v153, 0x24004, v151
	v_add_u32_e32 v173, 0x2401c, v151
	v_add_u32_e32 v203, 0x24024, v151
	ds_read2_b32 v[128:129], v128 offset1:1
	ds_read2_b32 v[154:155], v154 offset1:1
	ds_read2_b32 v[156:157], v156 offset1:1
	ds_read2_b32 v[158:159], v158 offset1:1
	ds_read2_b32 v[182:183], v127 offset1:1
	ds_read2_b32 v[184:185], v153 offset1:1
	ds_read2_b32 v[204:205], v173 offset1:1
	ds_read2_b32 v[206:207], v203 offset1:1
	s_waitcnt lgkmcnt(4)
	v_pk_add_f32 v[94:95], v[94:95], v[158:159]
	v_pk_add_f32 v[92:93], v[92:93], v[156:157]
	v_pk_add_f32 v[90:91], v[90:91], v[154:155]
	v_pk_add_f32 v[88:89], v[88:89], v[128:129]
	s_waitcnt lgkmcnt(0)
	v_pk_add_f32 v[86:87], v[86:87], v[206:207]
	v_pk_add_f32 v[84:85], v[84:85], v[204:205]
	v_pk_add_f32 v[82:83], v[82:83], v[184:185]
	v_pk_add_f32 v[80:81], v[80:81], v[182:183]
